# MLA step B: one softmax half-part per MFMA gap as in step A; K fragments d0=2 and d0=4 read into the loop-dead registers v[98:109]
# speedup vs baseline: 1.0179x; 1.0046x over previous
.LBB0_287:
	v_lshl_add_u64 v[50:51], s[80:81], 0, v[222:223]
	global_load_dwordx4 v[178:181], v[50:51], off
	s_waitcnt lgkmcnt(3)
	v_mfma_f32_32x32x16_bf16 v[50:65], v[68:71], v[166:169], v[34:49]
	ds_read_b128 v[90:93], v254 offset:2048
	ds_read_b128 v[94:97], v254 offset:2560
	v_exp_f32_e32 v114, v114
	v_exp_f32_e32 v115, v115
	v_add_f32_e32 v236, v66, v114
	v_cvt_pk_bf16_f32 v114, v114, v115
	v_add_f32_e32 v237, v67, v115
	s_waitcnt lgkmcnt(4)
	v_mfma_f32_32x32x16_bf16 v[66:81], v[86:89], v[166:169], v[34:49]
	v_exp_f32_e32 v116, v116
	v_exp_f32_e32 v117, v117
	v_add_f32_e32 v236, v236, v116
	v_cvt_pk_bf16_f32 v115, v116, v117
	v_add_f32_e32 v237, v237, v117
	s_waitcnt lgkmcnt(1)
	v_mfma_f32_32x32x16_bf16 v[50:65], v[90:93], v[162:165], v[50:65]
	ds_read_b128 v[98:101], v254 offset:4096
	ds_read_b128 v[190:193], v254 offset:4608
	v_exp_f32_e32 v118, v118
	v_exp_f32_e32 v119, v119
	v_add_f32_e32 v236, v236, v118
	v_cvt_pk_bf16_f32 v116, v118, v119
	v_add_f32_e32 v237, v237, v119
	s_waitcnt lgkmcnt(2)
	v_mfma_f32_32x32x16_bf16 v[66:81], v[94:97], v[162:165], v[66:81]
	v_exp_f32_e32 v120, v120
	v_exp_f32_e32 v121, v121
	v_add_f32_e32 v236, v236, v120
	v_cvt_pk_bf16_f32 v117, v120, v121
	v_add_f32_e32 v237, v237, v121
	s_waitcnt lgkmcnt(1)
	v_mfma_f32_32x32x16_bf16 v[50:65], v[98:101], v[158:161], v[50:65]
	ds_read_b128 v[88:91], v254 offset:6144
	ds_read_b128 v[92:95], v254 offset:6656
	v_exp_f32_e32 v122, v122
	v_exp_f32_e32 v123, v123
	v_add_f32_e32 v236, v236, v122
	v_cvt_pk_bf16_f32 v118, v122, v123
	v_add_f32_e32 v237, v237, v123
	s_waitcnt lgkmcnt(2)
	v_mfma_f32_32x32x16_bf16 v[66:81], v[190:193], v[158:161], v[66:81]
	v_exp_f32_e32 v124, v124
	v_exp_f32_e32 v125, v125
	v_add_f32_e32 v236, v236, v124
	v_cvt_pk_bf16_f32 v119, v124, v125
	v_add_f32_e32 v237, v237, v125
	s_waitcnt lgkmcnt(1)
	v_mfma_f32_32x32x16_bf16 v[50:65], v[88:91], v[154:157], v[50:65]
	ds_read_b128 v[102:105], v254 offset:8192
	ds_read_b128 v[106:109], v254 offset:8704
	v_exp_f32_e32 v126, v126
	v_exp_f32_e32 v127, v127
	v_add_f32_e32 v236, v236, v126
	v_cvt_pk_bf16_f32 v120, v126, v127
	v_add_f32_e32 v237, v237, v127
	s_waitcnt lgkmcnt(2)
	v_mfma_f32_32x32x16_bf16 v[66:81], v[92:95], v[154:157], v[66:81]
	v_exp_f32_e32 v128, v128
	v_exp_f32_e32 v129, v129
	v_add_f32_e32 v236, v236, v128
	v_cvt_pk_bf16_f32 v121, v128, v129
	v_add_f32_e32 v237, v237, v129
	s_waitcnt lgkmcnt(1)
	v_mfma_f32_32x32x16_bf16 v[50:65], v[102:105], v[150:153], v[50:65]
	ds_read_b128 v[88:91], v254 offset:10240
	ds_read_b128 v[92:95], v254 offset:10752
	v_exp_f32_e32 v130, v130
	v_exp_f32_e32 v131, v131
	v_add_f32_e32 v236, v236, v130
	v_cvt_pk_bf16_f32 v84, v130, v131
	v_add_f32_e32 v237, v237, v131
	s_waitcnt lgkmcnt(2)
	v_mfma_f32_32x32x16_bf16 v[66:81], v[106:109], v[150:153], v[66:81]
	v_exp_f32_e32 v132, v132
	v_exp_f32_e32 v133, v133
	v_add_f32_e32 v236, v236, v132
	v_cvt_pk_bf16_f32 v85, v132, v133
	v_add_f32_e32 v237, v237, v133
	s_waitcnt lgkmcnt(1)
	v_mfma_f32_32x32x16_bf16 v[50:65], v[88:91], v[146:149], v[50:65]
	v_exp_f32_e32 v134, v134
	v_exp_f32_e32 v135, v135
	v_add_f32_e32 v236, v236, v134
	v_cvt_pk_bf16_f32 v86, v134, v135
	v_add_f32_e32 v237, v237, v135
	s_waitcnt lgkmcnt(0)
	v_mfma_f32_32x32x16_bf16 v[66:81], v[92:95], v[146:149], v[66:81]
	ds_read_b64_tr_b16 v[88:89], v243 offset:40960
	ds_read_b64_tr_b16 v[90:91], v243 offset:41472
	ds_read_b64_tr_b16 v[92:93], v243 offset:45056
	ds_read_b64_tr_b16 v[94:95], v243 offset:45568
	v_exp_f32_e32 v136, v136
	v_exp_f32_e32 v137, v137
	v_add_f32_e32 v236, v236, v136
	v_cvt_pk_bf16_f32 v87, v136, v137
	v_add_f32_e32 v237, v237, v137
	s_waitcnt lgkmcnt(2)
	v_mfma_f32_32x32x16_bf16 v[18:33], v[114:117], v[88:91], v[18:33]
	ds_read_b64_tr_b16 v[126:127], v243 offset:41984
	ds_read_b64_tr_b16 v[128:129], v243 offset:42496
	v_exp_f32_e32 v138, v138
	v_exp_f32_e32 v139, v139
	v_add_f32_e32 v236, v236, v138
	v_cvt_pk_bf16_f32 v122, v138, v139
	v_add_f32_e32 v237, v237, v139
	s_waitcnt lgkmcnt(2)
	v_mfma_f32_32x32x16_bf16 v[2:17], v[114:117], v[92:95], v[2:17]
	ds_read_b64_tr_b16 v[88:89], v243 offset:46080
	ds_read_b64_tr_b16 v[90:91], v243 offset:46592
	v_exp_f32_e32 v140, v140
	v_exp_f32_e32 v141, v141
	v_add_f32_e32 v236, v236, v140
	v_cvt_pk_bf16_f32 v123, v140, v141
	v_add_f32_e32 v237, v237, v141
	s_waitcnt lgkmcnt(2)
	v_mfma_f32_32x32x16_bf16 v[18:33], v[118:121], v[126:129], v[18:33]
	ds_read_b64_tr_b16 v[92:93], v243 offset:43008
	ds_read_b64_tr_b16 v[94:95], v243 offset:43520
	v_exp_f32_e32 v142, v142
	v_exp_f32_e32 v143, v143
	v_add_f32_e32 v236, v236, v142
	v_cvt_pk_bf16_f32 v124, v142, v143
	v_add_f32_e32 v237, v237, v143
	s_waitcnt lgkmcnt(2)
	v_mfma_f32_32x32x16_bf16 v[2:17], v[118:121], v[88:91], v[2:17]
	ds_read_b64_tr_b16 v[114:115], v243 offset:47104
	ds_read_b64_tr_b16 v[116:117], v243 offset:47616
	v_exp_f32_e32 v144, v144
	v_exp_f32_e32 v145, v145
	v_add_f32_e32 v130, v236, v144
	v_cvt_pk_bf16_f32 v125, v144, v145
	v_add_f32_e32 v131, v237, v145
	s_waitcnt lgkmcnt(2)
	v_mfma_f32_32x32x16_bf16 v[18:33], v[84:87], v[92:95], v[18:33]
	ds_read_b64_tr_b16 v[88:89], v243 offset:44032
	ds_read_b64_tr_b16 v[90:91], v243 offset:44544
	v_max_f32_e32 v83, v50, v50
	v_max_f32_e32 v83, 0xf149f2ca, v83
	v_max3_f32 v96, v66, s25, v67
	v_max3_f32 v83, v83, v51, v52
	v_max3_f32 v96, v96, v68, v69
	s_waitcnt lgkmcnt(2)
	v_mfma_f32_32x32x16_bf16 v[2:17], v[84:87], v[114:117], v[2:17]
	ds_read_b64_tr_b16 v[92:93], v243 offset:48128
	ds_read_b64_tr_b16 v[94:95], v243 offset:48640
	v_max3_f32 v83, v83, v53, v54
	v_max3_f32 v96, v96, v70, v71
	v_max3_f32 v83, v83, v55, v56
	v_max3_f32 v96, v96, v72, v73
	s_waitcnt lgkmcnt(2)
	v_mfma_f32_32x32x16_bf16 v[18:33], v[122:125], v[88:91], v[18:33]
	v_max3_f32 v83, v83, v57, v58
	v_max3_f32 v96, v96, v74, v75
	v_max3_f32 v83, v83, v59, v60
	v_max3_f32 v96, v96, v76, v77
	s_waitcnt lgkmcnt(0)
	v_mfma_f32_32x32x16_bf16 v[2:17], v[122:125], v[92:95], v[2:17]
	v_max3_f32 v83, v83, v61, v62
	v_max3_f32 v96, v96, v78, v79
	v_max3_f32 v83, v83, v63, v64
	v_max3_f32 v96, v96, v80, v81
	s_add_i32 s36, s36, 2
	v_max3_f32 v83, v83, v65, v96
	v_lshl_add_u64 v[218:219], v[218:219], 0, s[38:39]
	v_lshl_add_u64 v[220:221], v[220:221], 0, s[82:83]
	v_lshl_add_u64 v[222:223], v[222:223], 0, s[82:83]
	s_cmpk_gt_u32 s36, 0x7d
	v_lshl_add_u64 v[224:225], v[224:225], 0, s[82:83]
	s_barrier
	s_cbranch_scc1 .LBB0_305
